# attention loop: running-max registers updated only when a row max moves (no per-iteration copies), with scalar-base K/V prefetch and rewritten conversion slice
# baseline (speedup 1.0000x reference)
.LBB0_452:
	s_setprio 2
	v_add3_u32 v197, s54, v190, v215
	ds_read_b128 v[68:71], v197
	ds_read_b128 v[72:75], v197 offset:32
	ds_read_b128 v[76:79], v197 offset:64
	ds_read_b128 v[80:83], v197 offset:96
	ds_read_b128 v[84:87], v197 offset:4608
	ds_read_b128 v[88:91], v197 offset:4640
	ds_read_b128 v[92:95], v197 offset:4672
	ds_read_b128 v[96:99], v197 offset:4704
	global_load_dwordx4 v[136:139], v246, s[60:61]
	global_load_dwordx4 v[140:143], v246, s[62:63]
	s_waitcnt lgkmcnt(7)
	v_mfma_f32_32x32x16_bf16 v[100:115], v[68:71], v[132:135], 0
	global_load_dwordx4 v[176:179], v247, s[64:65]
	global_load_dwordx4 v[144:147], v247, s[66:67]
	s_waitcnt lgkmcnt(6)
	v_mfma_f32_32x32x16_bf16 v[100:115], v[72:75], v[156:159], v[100:115]
	v_add3_u32 v210, s54, v188, v65
	v_add_u32_e32 v211, 0x3000, v210
	s_waitcnt lgkmcnt(5)
	v_mfma_f32_32x32x16_bf16 v[100:115], v[76:79], v[152:155], v[100:115]
	v_add_u32_e32 v210, 0x2000, v210
	s_waitcnt lgkmcnt(4)
	v_mfma_f32_32x32x16_bf16 v[100:115], v[80:83], v[148:151], v[100:115]
	s_waitcnt lgkmcnt(3)
	v_mfma_f32_32x32x16_bf16 v[116:131], v[84:87], v[132:135], 0
	s_waitcnt lgkmcnt(2)
	v_mfma_f32_32x32x16_bf16 v[116:131], v[88:91], v[156:159], v[116:131]
	s_waitcnt lgkmcnt(1)
	v_mfma_f32_32x32x16_bf16 v[116:131], v[92:95], v[152:155], v[116:131]
	s_waitcnt lgkmcnt(0)
	v_mfma_f32_32x32x16_bf16 v[116:131], v[96:99], v[148:151], v[116:131]
	ds_read_b128 v[202:205], v197 offset:4608
	ds_read_b128 v[206:209], v197 offset:4640
	ds_read_b128 v[218:221], v197 offset:4672
	v_mfma_f32_32x32x16_bf16 v[84:99], v[68:71], v[172:175], 0
	v_max3_f32 v67, v100, v101, v102
	v_max3_f32 v67, v67, v103, v104
	v_mfma_f32_32x32x16_bf16 v[84:99], v[72:75], v[168:171], v[84:99]
	v_max3_f32 v67, v67, v105, v106
	v_max3_f32 v67, v67, v107, v108
	v_mfma_f32_32x32x16_bf16 v[84:99], v[76:79], v[164:167], v[84:99]
	v_max3_f32 v67, v67, v109, v110
	v_max3_f32 v67, v67, v111, v112
	v_mfma_f32_32x32x16_bf16 v[84:99], v[80:83], v[160:163], v[84:99]
	v_max3_f32 v67, v67, v113, v114
	v_max_f32_e32 v67, v67, v115
	s_waitcnt lgkmcnt(2)
	v_mfma_f32_32x32x16_bf16 v[68:83], v[202:205], v[172:175], 0
	ds_read_b128 v[202:205], v197 offset:4704
	v_max3_f32 v182, v116, v117, v118
	v_max3_f32 v182, v182, v119, v120
	v_max3_f32 v182, v182, v121, v122
	v_max3_f32 v182, v182, v123, v124
	s_waitcnt lgkmcnt(2)
	v_mfma_f32_32x32x16_bf16 v[68:83], v[206:209], v[168:171], v[68:83]
	v_max3_f32 v182, v182, v125, v126
	v_max3_f32 v182, v182, v127, v128
	v_max3_f32 v182, v182, v129, v130
	v_max_f32_e32 v182, v182, v131
	v_max_f32_e32 v67, v67, v182
	ds_bpermute_b32 v182, v191, v67
	s_waitcnt lgkmcnt(2)
	v_mfma_f32_32x32x16_bf16 v[68:83], v[218:221], v[164:167], v[68:83]
	s_waitcnt lgkmcnt(1)
	v_mfma_f32_32x32x16_bf16 v[68:83], v[202:205], v[160:163], v[68:83]
	ds_read2_b64 v[206:209], v210 offset0:128 offset1:130
	ds_read2_b64 v[218:221], v211 offset0:160 offset1:162
	s_waitcnt lgkmcnt(2)
	v_max3_f32 v66, v216, v67, v182
	v_cmp_gt_f32_e32 vcc, v66, v216
	s_cbranch_vccz .Lattn_keep0
	v_sub_f32_e32 v182, v216, v66
	v_exp_f32_e32 v182, v182
	s_nop 0
	v_pk_mul_f32 v[48:49], v[48:49], v[182:183] op_sel_hi:[1,0]
	v_pk_mul_f32 v[50:51], v[50:51], v[182:183] op_sel_hi:[1,0]
	v_pk_mul_f32 v[52:53], v[52:53], v[182:183] op_sel_hi:[1,0]
	v_pk_mul_f32 v[54:55], v[54:55], v[182:183] op_sel_hi:[1,0]
	v_pk_mul_f32 v[56:57], v[56:57], v[182:183] op_sel_hi:[1,0]
	v_pk_mul_f32 v[58:59], v[58:59], v[182:183] op_sel_hi:[1,0]
	v_pk_mul_f32 v[60:61], v[60:61], v[182:183] op_sel_hi:[1,0]
	v_pk_mul_f32 v[62:63], v[62:63], v[182:183] op_sel_hi:[1,0]
	v_pk_mul_f32 v[16:17], v[16:17], v[182:183] op_sel_hi:[1,0]
	v_pk_mul_f32 v[18:19], v[18:19], v[182:183] op_sel_hi:[1,0]
	v_pk_mul_f32 v[20:21], v[20:21], v[182:183] op_sel_hi:[1,0]
	v_pk_mul_f32 v[22:23], v[22:23], v[182:183] op_sel_hi:[1,0]
	v_pk_mul_f32 v[24:25], v[24:25], v[182:183] op_sel_hi:[1,0]
	v_pk_mul_f32 v[26:27], v[26:27], v[182:183] op_sel_hi:[1,0]
	v_pk_mul_f32 v[28:29], v[28:29], v[182:183] op_sel_hi:[1,0]
	v_pk_mul_f32 v[30:31], v[30:31], v[182:183] op_sel_hi:[1,0]
	v_mul_f32_e32 v194, v194, v182
	v_mov_b32_e32 v216, v66
.Lattn_keep0:
	v_sub_f32_e32 v100, v100, v216
	v_sub_f32_e32 v101, v101, v216
	v_exp_f32_e32 v100, v100
	v_sub_f32_e32 v102, v102, v216
	v_exp_f32_e32 v101, v101
	v_max3_f32 v67, v84, v85, v86
	v_add_f32_e32 v194, v194, v100
	v_sub_f32_e32 v103, v103, v216
	v_exp_f32_e32 v102, v102
	v_add_f32_e32 v194, v194, v101
	v_sub_f32_e32 v104, v104, v216
	v_max3_f32 v67, v67, v87, v88
	v_exp_f32_e32 v103, v103
	v_add_f32_e32 v194, v194, v102
	v_sub_f32_e32 v105, v105, v216
	v_exp_f32_e32 v104, v104
	v_add_f32_e32 v194, v194, v103
	v_max3_f32 v67, v67, v89, v90
	v_sub_f32_e32 v106, v106, v216
	v_exp_f32_e32 v105, v105
	v_add_f32_e32 v194, v194, v104
	v_sub_f32_e32 v107, v107, v216
	v_exp_f32_e32 v106, v106
	v_max3_f32 v67, v67, v91, v92
	v_add_f32_e32 v194, v194, v105
	v_sub_f32_e32 v108, v108, v216
	v_exp_f32_e32 v107, v107
	v_add_f32_e32 v194, v194, v106
	v_sub_f32_e32 v109, v109, v216
	v_max3_f32 v67, v67, v93, v94
	v_exp_f32_e32 v108, v108
	v_add_f32_e32 v194, v194, v107
	v_cvt_pk_bf16_f32 v100, v100, v101
	v_cvt_pk_bf16_f32 v101, v102, v103
	v_cvt_pk_bf16_f32 v102, v104, v105
	v_max3_f32 v67, v67, v95, v96
	v_cvt_pk_bf16_f32 v103, v106, v107
	ds_read2_b64 v[202:205], v210 offset0:132 offset1:134
	ds_read2_b64 v[104:107], v211 offset0:164 offset1:166
	v_sub_f32_e32 v110, v110, v216
	v_exp_f32_e32 v109, v109
	s_waitcnt lgkmcnt(3)
	v_mfma_f32_32x32x16_bf16 v[48:63], v[206:209], v[100:103], v[48:63]
	v_add_f32_e32 v194, v194, v108
	v_sub_f32_e32 v111, v111, v216
	v_max3_f32 v67, v67, v97, v98
	v_exp_f32_e32 v110, v110
	v_add_f32_e32 v194, v194, v109
	v_sub_f32_e32 v112, v112, v216
	v_exp_f32_e32 v111, v111
	v_add_f32_e32 v194, v194, v110
	v_max_f32_e32 v67, v67, v99
	v_sub_f32_e32 v113, v113, v216
	v_exp_f32_e32 v112, v112
	v_add_f32_e32 v194, v194, v111
	s_waitcnt lgkmcnt(2)
	v_mfma_f32_32x32x16_bf16 v[16:31], v[218:221], v[100:103], v[16:31]
	v_sub_f32_e32 v114, v114, v216
	v_exp_f32_e32 v113, v113
	v_max3_f32 v182, v68, v69, v70
	v_add_f32_e32 v194, v194, v112
	v_sub_f32_e32 v115, v115, v216
	v_exp_f32_e32 v114, v114
	v_add_f32_e32 v194, v194, v113
	v_sub_f32_e32 v116, v116, v216
	v_max3_f32 v182, v182, v71, v72
	v_exp_f32_e32 v115, v115
	v_add_f32_e32 v194, v194, v114
	v_sub_f32_e32 v117, v117, v216
	v_exp_f32_e32 v116, v116
	v_add_f32_e32 v194, v194, v115
	v_max3_f32 v182, v182, v73, v74
	v_cvt_pk_bf16_f32 v108, v108, v109
	v_cvt_pk_bf16_f32 v109, v110, v111
	v_cvt_pk_bf16_f32 v110, v112, v113
	v_cvt_pk_bf16_f32 v111, v114, v115
	ds_read2_b64 v[206:209], v210 offset0:136 offset1:138
	ds_read2_b64 v[218:221], v211 offset0:168 offset1:170
	v_sub_f32_e32 v118, v118, v216
	v_max3_f32 v182, v182, v75, v76
	v_exp_f32_e32 v117, v117
	s_waitcnt lgkmcnt(3)
	v_mfma_f32_32x32x16_bf16 v[48:63], v[202:205], v[108:111], v[48:63]
	v_add_f32_e32 v194, v194, v116
	v_sub_f32_e32 v119, v119, v216
	v_exp_f32_e32 v118, v118
	v_add_f32_e32 v194, v194, v117
	v_max3_f32 v182, v182, v77, v78
	v_sub_f32_e32 v120, v120, v216
	v_exp_f32_e32 v119, v119
	v_add_f32_e32 v194, v194, v118
	v_sub_f32_e32 v121, v121, v216
	v_exp_f32_e32 v120, v120
	v_max3_f32 v182, v182, v79, v80
	v_add_f32_e32 v194, v194, v119
	s_waitcnt lgkmcnt(2)
	v_mfma_f32_32x32x16_bf16 v[16:31], v[104:107], v[108:111], v[16:31]
	v_sub_f32_e32 v122, v122, v216
	v_exp_f32_e32 v121, v121
	v_add_f32_e32 v194, v194, v120
	v_sub_f32_e32 v123, v123, v216
	v_max3_f32 v182, v182, v81, v82
	v_exp_f32_e32 v122, v122
	v_add_f32_e32 v194, v194, v121
	v_sub_f32_e32 v124, v124, v216
	v_exp_f32_e32 v123, v123
	v_add_f32_e32 v194, v194, v122
	v_max_f32_e32 v182, v182, v83
	v_sub_f32_e32 v125, v125, v216
	v_exp_f32_e32 v124, v124
	v_add_f32_e32 v194, v194, v123
	v_cvt_pk_bf16_f32 v116, v116, v117
	v_cvt_pk_bf16_f32 v117, v118, v119
	v_max_f32_e32 v67, v67, v182
	v_cvt_pk_bf16_f32 v118, v120, v121
	v_cvt_pk_bf16_f32 v119, v122, v123
	ds_read2_b64 v[112:115], v210 offset0:140 offset1:142
	ds_read2_b64 v[202:205], v211 offset0:172 offset1:174
	v_sub_f32_e32 v126, v126, v216
	v_exp_f32_e32 v125, v125
	s_waitcnt lgkmcnt(3)
	v_mfma_f32_32x32x16_bf16 v[48:63], v[206:209], v[116:119], v[48:63]
	v_add_f32_e32 v194, v194, v124
	ds_bpermute_b32 v182, v191, v67
	v_sub_f32_e32 v127, v127, v216
	v_exp_f32_e32 v126, v126
	v_add_f32_e32 v194, v194, v125
	v_sub_f32_e32 v128, v128, v216
	v_exp_f32_e32 v127, v127
	v_add_f32_e32 v194, v194, v126
	v_sub_f32_e32 v129, v129, v216
	v_exp_f32_e32 v128, v128
	v_add_f32_e32 v194, v194, v127
	s_waitcnt lgkmcnt(3)
	v_mfma_f32_32x32x16_bf16 v[16:31], v[218:221], v[116:119], v[16:31]
	v_sub_f32_e32 v130, v130, v216
	v_exp_f32_e32 v129, v129
	v_add_f32_e32 v194, v194, v128
	v_sub_f32_e32 v131, v131, v216
	v_exp_f32_e32 v130, v130
	v_add_f32_e32 v194, v194, v129
	v_exp_f32_e32 v131, v131
	v_add_f32_e32 v194, v194, v130
	v_add_f32_e32 v194, v194, v131
	v_cvt_pk_bf16_f32 v124, v124, v125
	v_cvt_pk_bf16_f32 v125, v126, v127
	v_cvt_pk_bf16_f32 v126, v128, v129
	v_cvt_pk_bf16_f32 v127, v130, v131
	ds_read2_b64 v[104:107], v210 offset0:128 offset1:130
	ds_read2_b64 v[120:123], v211 offset0:160 offset1:162
	s_nop 1
	s_waitcnt lgkmcnt(4)
	v_mfma_f32_32x32x16_bf16 v[48:63], v[112:115], v[124:127], v[48:63]
	s_waitcnt lgkmcnt(3)
	v_mfma_f32_32x32x16_bf16 v[16:31], v[202:205], v[124:127], v[16:31]
	s_waitcnt lgkmcnt(2)
	v_max3_f32 v64, v217, v67, v182
	v_cmp_gt_f32_e32 vcc, v64, v217
	s_cbranch_vccz .Lattn_keep1
	v_sub_f32_e32 v182, v217, v64
	v_exp_f32_e32 v182, v182
	s_nop 0
	v_pk_mul_f32 v[32:33], v[32:33], v[182:183] op_sel_hi:[1,0]
	v_pk_mul_f32 v[34:35], v[34:35], v[182:183] op_sel_hi:[1,0]
	v_pk_mul_f32 v[36:37], v[36:37], v[182:183] op_sel_hi:[1,0]
	v_pk_mul_f32 v[38:39], v[38:39], v[182:183] op_sel_hi:[1,0]
	v_pk_mul_f32 v[40:41], v[40:41], v[182:183] op_sel_hi:[1,0]
	v_pk_mul_f32 v[42:43], v[42:43], v[182:183] op_sel_hi:[1,0]
	v_pk_mul_f32 v[44:45], v[44:45], v[182:183] op_sel_hi:[1,0]
	v_pk_mul_f32 v[46:47], v[46:47], v[182:183] op_sel_hi:[1,0]
	v_pk_mul_f32 v[0:1], v[0:1], v[182:183] op_sel_hi:[1,0]
	v_pk_mul_f32 v[2:3], v[2:3], v[182:183] op_sel_hi:[1,0]
	v_pk_mul_f32 v[4:5], v[4:5], v[182:183] op_sel_hi:[1,0]
	v_pk_mul_f32 v[6:7], v[6:7], v[182:183] op_sel_hi:[1,0]
	v_pk_mul_f32 v[8:9], v[8:9], v[182:183] op_sel_hi:[1,0]
	v_pk_mul_f32 v[10:11], v[10:11], v[182:183] op_sel_hi:[1,0]
	v_pk_mul_f32 v[12:13], v[12:13], v[182:183] op_sel_hi:[1,0]
	v_pk_mul_f32 v[14:15], v[14:15], v[182:183] op_sel_hi:[1,0]
	v_mul_f32_e32 v195, v195, v182
	v_mov_b32_e32 v217, v64
.Lattn_keep1:
	v_sub_f32_e32 v84, v84, v217
	v_sub_f32_e32 v85, v85, v217
	v_exp_f32_e32 v84, v84
	v_sub_f32_e32 v86, v86, v217
	v_exp_f32_e32 v85, v85
	v_add_f32_e32 v195, v195, v84
	v_sub_f32_e32 v87, v87, v217
	v_exp_f32_e32 v86, v86
	v_add_f32_e32 v195, v195, v85
	v_sub_f32_e32 v88, v88, v217
	v_exp_f32_e32 v87, v87
	v_add_f32_e32 v195, v195, v86
	v_sub_f32_e32 v89, v89, v217
	v_exp_f32_e32 v88, v88
	v_add_f32_e32 v195, v195, v87
	v_sub_f32_e32 v90, v90, v217
	v_exp_f32_e32 v89, v89
	v_add_f32_e32 v195, v195, v88
	v_sub_f32_e32 v91, v91, v217
	v_exp_f32_e32 v90, v90
	v_add_f32_e32 v195, v195, v89
	v_sub_f32_e32 v92, v92, v217
	v_exp_f32_e32 v91, v91
	v_add_f32_e32 v195, v195, v90
	v_sub_f32_e32 v93, v93, v217
	v_exp_f32_e32 v92, v92
	v_add_f32_e32 v195, v195, v91
	v_cvt_pk_bf16_f32 v84, v84, v85
	v_cvt_pk_bf16_f32 v85, v86, v87
	v_cvt_pk_bf16_f32 v86, v88, v89
	v_cvt_pk_bf16_f32 v87, v90, v91
	ds_read2_b64 v[206:209], v210 offset0:132 offset1:134
	ds_read2_b64 v[218:221], v211 offset0:164 offset1:166
	v_sub_f32_e32 v94, v94, v217
	v_exp_f32_e32 v93, v93
	s_waitcnt lgkmcnt(3)
	v_mfma_f32_32x32x16_bf16 v[32:47], v[104:107], v[84:87], v[32:47]
	v_add_f32_e32 v195, v195, v92
	v_sub_f32_e32 v95, v95, v217
	v_exp_f32_e32 v94, v94
	v_add_f32_e32 v195, v195, v93
	v_sub_f32_e32 v96, v96, v217
	v_exp_f32_e32 v95, v95
	v_add_f32_e32 v195, v195, v94
	v_sub_f32_e32 v97, v97, v217
	v_exp_f32_e32 v96, v96
	v_add_f32_e32 v195, v195, v95
	s_waitcnt lgkmcnt(2)
	v_mfma_f32_32x32x16_bf16 v[0:15], v[120:123], v[84:87], v[0:15]
	v_sub_f32_e32 v98, v98, v217
	v_exp_f32_e32 v97, v97
	v_add_f32_e32 v195, v195, v96
	v_sub_f32_e32 v99, v99, v217
	v_exp_f32_e32 v98, v98
	v_add_f32_e32 v195, v195, v97
	v_sub_f32_e32 v68, v68, v217
	v_exp_f32_e32 v99, v99
	v_add_f32_e32 v195, v195, v98
	v_sub_f32_e32 v69, v69, v217
	v_exp_f32_e32 v68, v68
	v_add_f32_e32 v195, v195, v99
	v_cvt_pk_bf16_f32 v92, v92, v93
	v_cvt_pk_bf16_f32 v93, v94, v95
	v_cvt_pk_bf16_f32 v94, v96, v97
	v_cvt_pk_bf16_f32 v95, v98, v99
	ds_read2_b64 v[128:131], v210 offset0:136 offset1:138
	ds_read2_b64 v[112:115], v211 offset0:168 offset1:170
	v_sub_f32_e32 v70, v70, v217
	v_exp_f32_e32 v69, v69
	s_waitcnt lgkmcnt(3)
	v_mfma_f32_32x32x16_bf16 v[32:47], v[206:209], v[92:95], v[32:47]
	v_add_f32_e32 v195, v195, v68
	v_sub_f32_e32 v71, v71, v217
	v_exp_f32_e32 v70, v70
	v_add_f32_e32 v195, v195, v69
	v_sub_f32_e32 v72, v72, v217
	v_exp_f32_e32 v71, v71
	v_add_f32_e32 v195, v195, v70
	v_sub_f32_e32 v73, v73, v217
	v_exp_f32_e32 v72, v72
	v_add_f32_e32 v195, v195, v71
	s_waitcnt lgkmcnt(2)
	v_mfma_f32_32x32x16_bf16 v[0:15], v[218:221], v[92:95], v[0:15]
	v_sub_f32_e32 v74, v74, v217
	v_exp_f32_e32 v73, v73
	v_add_f32_e32 v195, v195, v72
	v_sub_f32_e32 v75, v75, v217
	v_exp_f32_e32 v74, v74
	v_add_f32_e32 v195, v195, v73
	v_sub_f32_e32 v76, v76, v217
	v_exp_f32_e32 v75, v75
	v_add_f32_e32 v195, v195, v74
	v_sub_f32_e32 v77, v77, v217
	v_exp_f32_e32 v76, v76
	v_add_f32_e32 v195, v195, v75
	v_cvt_pk_bf16_f32 v68, v68, v69
	v_cvt_pk_bf16_f32 v69, v70, v71
	v_cvt_pk_bf16_f32 v70, v72, v73
	v_cvt_pk_bf16_f32 v71, v74, v75
	ds_read2_b64 v[202:205], v210 offset0:140 offset1:142
	ds_read2_b64 v[88:91], v211 offset0:172 offset1:174
	v_sub_f32_e32 v78, v78, v217
	v_exp_f32_e32 v77, v77
	s_waitcnt lgkmcnt(3)
	v_mfma_f32_32x32x16_bf16 v[32:47], v[128:131], v[68:71], v[32:47]
	v_add_f32_e32 v195, v195, v76
	v_sub_f32_e32 v79, v79, v217
	v_exp_f32_e32 v78, v78
	v_add_f32_e32 v195, v195, v77
	v_sub_f32_e32 v80, v80, v217
	v_exp_f32_e32 v79, v79
	v_add_f32_e32 v195, v195, v78
	v_sub_f32_e32 v81, v81, v217
	v_exp_f32_e32 v80, v80
	v_add_f32_e32 v195, v195, v79
	s_waitcnt lgkmcnt(2)
	v_mfma_f32_32x32x16_bf16 v[0:15], v[112:115], v[68:71], v[0:15]
	v_sub_f32_e32 v82, v82, v217
	v_exp_f32_e32 v81, v81
	v_add_f32_e32 v195, v195, v80
	v_sub_f32_e32 v83, v83, v217
	v_exp_f32_e32 v82, v82
	v_add_f32_e32 v195, v195, v81
	v_exp_f32_e32 v83, v83
	v_add_f32_e32 v195, v195, v82
	v_add_f32_e32 v195, v195, v83
	v_cvt_pk_bf16_f32 v76, v76, v77
	v_cvt_pk_bf16_f32 v77, v78, v79
	v_cvt_pk_bf16_f32 v78, v80, v81
	v_cvt_pk_bf16_f32 v79, v82, v83
	s_nop 1
	s_waitcnt lgkmcnt(1)
	v_mfma_f32_32x32x16_bf16 v[32:47], v[202:205], v[76:79], v[32:47]
	s_waitcnt lgkmcnt(0)
	v_mfma_f32_32x32x16_bf16 v[0:15], v[88:91], v[76:79], v[0:15]
	s_bitcmp1_b32 s50, 0
	s_cselect_b32 s0, 0x4600, 0
	s_add_i32 s53, s53, s33
	s_addk_i32 s52, 0x4000
	s_add_i32 s50, s50, 1
	s_add_u32 s60, s60, 0x2000
	s_addc_u32 s61, s61, 0
	s_add_u32 s62, s62, 0x2000
	s_addc_u32 s63, s63, 0
	s_add_u32 s64, s64, 0x80
	s_addc_u32 s65, s65, 0
	s_add_u32 s66, s66, 0x80
	s_addc_u32 s67, s67, 0
	s_cmpk_lg_i32 s50, 0x44
	v_add_u32_e32 v67, s0, v192
	v_add_u32_e32 v182, s0, v196
	v_add_u32_e32 v197, 0x2400, v182
	v_add_u32_e32 v182, 0x3500, v182
	s_waitcnt vmcnt(0)
	ds_write_b128 v67, v[136:139]
	ds_write_b128 v67, v[140:143] offset:4608
	ds_write2_b64 v197, v[176:177], v[178:179] offset1:1
	ds_write2_b64 v182, v[144:145], v[146:147] offset1:1
	s_waitcnt lgkmcnt(0)
	s_barrier
	s_cbranch_scc0 .LBB0_460
	s_branch .LBB0_430
.LBB0_460:
	s_setprio 0
	v_mov_b32_e32 v66, v216
	v_mov_b32_e32 v64, v217
	s_cmpk_lt_i32 s25, 0x43
	s_cbranch_scc1 .LBB0_471
	s_add_i32 s0, s31, 0x42
	s_mul_i32 s0, s0, s33
	v_readlane_b32 s4, v255, 0
	s_add_i32 s0, s0, s4
	s_cmpk_lt_i32 s0, 0x6400
	s_cselect_b32 s49, s0, -1
	s_cmp_lt_i32 s49, 0
	v_readlane_b32 s5, v255, 1
	s_cbranch_scc1 .LBB0_471
	s_cmpk_lt_u32 s49, 0x300
	s_mov_b64 s[26:27], -1
	s_cbranch_scc1 .LBB0_468
	s_cmpk_lt_u32 s49, 0x400
	s_cbranch_scc1 .LBB0_465
	s_add_i32 s0, s49, 0xfffffc00
	s_and_b32 s4, s0, 0xffffe000
	s_cmpk_eq_i32 s4, 0x2000
	s_cselect_b32 s4, s45, 0x8ca0000
	s_cmpk_gt_u32 s0, 0x1fff
	s_cselect_b32 s4, s4, 0xca0000
	s_add_u32 s4, s94, s4
	s_addc_u32 s5, s95, 0
	s_lshl_b32 s0, s0, 13
	s_and_b32 s0, s0, 0x3e00000
	s_add_u32 s4, s4, s0
	s_addc_u32 s5, s5, 0
	s_lshl_b32 s0, s49, 2
	s_lshl_b32 s25, s49, 6
	s_and_b32 s0, s0, 0x3c0
	s_and_b32 s25, s25, 0x3c0
	s_mov_b64 s[26:27], 0
